# conversion phases: waves of a workgroup start the transpose loops staggered by about 1us each (s_sleep) so loads and LDS transposes of different waves overlap; on top of v5
# speedup vs baseline: 1.0024x; 1.0024x over previous
.LBB0_40:
	s_or_b64 exec, exec, s[24:25]
	s_ashr_i32 s0, s33, 6
	s_mov_b32 s100, s0
.Lstg0_loop:
	s_cmp_eq_u32 s100, 0
	s_cbranch_scc1 .Lstg0_done
	s_sleep 32
	s_sub_u32 s100, s100, 1
	s_branch .Lstg0_loop
.Lstg0_done:
	v_lshrrev_b32_e32 v72, 5, v36
	s_lshl_b32 s1, s0, 14
	v_bitop3_b32 v5, v72, v1, 31 bitop3:0x78
	s_add_i32 s1, s1, 0
	v_and_b32_e32 v2, 31, v1
	v_lshlrev_b32_e32 v6, 7, v72
	v_lshlrev_b32_e32 v5, 2, v5
	v_or_b32_e32 v74, 2, v72
	v_add3_u32 v105, s1, v6, v5
	v_bitop3_b32 v6, v72, v2, 2 bitop3:0x36
	v_lshlrev_b32_e32 v7, 7, v74
	v_lshlrev_b32_e32 v6, 2, v6
	v_or_b32_e32 v75, 4, v72
	v_add3_u32 v106, s1, v7, v6
	v_bitop3_b32 v6, v72, v2, 4 bitop3:0x36
	v_lshlrev_b32_e32 v7, 7, v75
	v_lshlrev_b32_e32 v6, 2, v6
	v_or_b32_e32 v76, 6, v72
	v_add3_u32 v107, s1, v7, v6
	v_bitop3_b32 v6, v72, v2, 6 bitop3:0x36
	v_lshlrev_b32_e32 v7, 7, v76
	v_lshlrev_b32_e32 v6, 2, v6
	v_or_b32_e32 v77, 8, v72
	v_add3_u32 v108, s1, v7, v6
	v_bitop3_b32 v6, v72, v2, 8 bitop3:0x36
	v_lshlrev_b32_e32 v7, 7, v77
	v_lshlrev_b32_e32 v6, 2, v6
	v_or_b32_e32 v78, 10, v72
	v_add3_u32 v109, s1, v7, v6
	v_bitop3_b32 v6, v72, v2, 10 bitop3:0x36
	v_lshlrev_b32_e32 v7, 7, v78
	v_lshlrev_b32_e32 v6, 2, v6
	v_or_b32_e32 v79, 12, v72
	v_add3_u32 v110, s1, v7, v6
	v_bitop3_b32 v6, v72, v2, 12 bitop3:0x36
	v_lshlrev_b32_e32 v7, 7, v79
	v_lshlrev_b32_e32 v6, 2, v6
	v_or_b32_e32 v80, 14, v72
	v_add3_u32 v111, s1, v7, v6
	v_bitop3_b32 v6, v72, v2, 14 bitop3:0x36
	v_lshlrev_b32_e32 v7, 7, v80
	v_lshlrev_b32_e32 v6, 2, v6
	v_or_b32_e32 v81, 16, v72
	v_add3_u32 v112, s1, v7, v6
	v_bitop3_b32 v6, v72, v2, 16 bitop3:0x36
	v_lshlrev_b32_e32 v7, 7, v81
	v_lshlrev_b32_e32 v6, 2, v6
	v_or_b32_e32 v82, 18, v72
	v_add3_u32 v113, s1, v7, v6
	v_bitop3_b32 v6, v72, v2, 18 bitop3:0x36
	v_lshlrev_b32_e32 v7, 7, v82
	v_lshlrev_b32_e32 v6, 2, v6
	v_or_b32_e32 v83, 20, v72
	v_add3_u32 v114, s1, v7, v6
	v_bitop3_b32 v6, v72, v2, 20 bitop3:0x36
	v_lshlrev_b32_e32 v7, 7, v83
	v_lshlrev_b32_e32 v6, 2, v6
	v_or_b32_e32 v84, 22, v72
	v_add3_u32 v115, s1, v7, v6
	v_bitop3_b32 v6, v72, v2, 22 bitop3:0x36
	v_lshlrev_b32_e32 v7, 7, v84
	v_lshlrev_b32_e32 v6, 2, v6
	v_or_b32_e32 v85, 24, v72
	v_add3_u32 v116, s1, v7, v6
	v_bitop3_b32 v6, v72, v2, 24 bitop3:0x36
	v_lshlrev_b32_e32 v7, 7, v85
	v_lshlrev_b32_e32 v6, 2, v6
	v_or_b32_e32 v86, 26, v72
	v_add3_u32 v117, s1, v7, v6
	v_bitop3_b32 v6, v72, v2, 26 bitop3:0x36
	v_lshlrev_b32_e32 v7, 7, v86
	v_lshlrev_b32_e32 v6, 2, v6
	v_or_b32_e32 v87, 28, v72
	v_add3_u32 v118, s1, v7, v6
	v_bitop3_b32 v6, v72, v2, 28 bitop3:0x36
	v_lshlrev_b32_e32 v7, 7, v87
	v_lshlrev_b32_e32 v6, 2, v6
	v_or_b32_e32 v88, 30, v72
	v_add3_u32 v119, s1, v7, v6
	v_bitop3_b32 v6, v72, v2, 30 bitop3:0x36
	v_or_b32_e32 v89, 32, v72
	v_lshlrev_b32_e32 v7, 7, v88
	v_lshlrev_b32_e32 v6, 2, v6
	v_or_b32_e32 v90, 34, v72
	v_add3_u32 v120, s1, v7, v6
	v_lshlrev_b32_e32 v6, 7, v89
	v_add3_u32 v121, s1, v6, v5
	v_bitop3_b32 v5, v90, 31, v1 bitop3:0x48
	v_or_b32_e32 v91, 36, v72
	v_lshlrev_b32_e32 v6, 7, v90
	v_lshlrev_b32_e32 v5, 2, v5
	v_add3_u32 v122, s1, v6, v5
	v_bitop3_b32 v5, v91, 31, v1 bitop3:0x48
	v_or_b32_e32 v92, 38, v72
	v_lshlrev_b32_e32 v6, 7, v91
	v_lshlrev_b32_e32 v5, 2, v5
	v_add3_u32 v123, s1, v6, v5
	v_bitop3_b32 v5, v92, 31, v1 bitop3:0x48
	v_or_b32_e32 v93, 40, v72
	v_lshlrev_b32_e32 v6, 7, v92
	v_lshlrev_b32_e32 v5, 2, v5
	v_add3_u32 v124, s1, v6, v5
	v_bitop3_b32 v5, v93, 31, v1 bitop3:0x48
	v_or_b32_e32 v94, 42, v72
	v_lshlrev_b32_e32 v6, 7, v93
	v_lshlrev_b32_e32 v5, 2, v5
	v_add3_u32 v125, s1, v6, v5
	v_bitop3_b32 v5, v94, 31, v1 bitop3:0x48
	v_or_b32_e32 v95, 44, v72
	v_lshlrev_b32_e32 v6, 7, v94
	v_lshlrev_b32_e32 v5, 2, v5
	v_add3_u32 v126, s1, v6, v5
	v_bitop3_b32 v5, v95, 31, v1 bitop3:0x48
	v_or_b32_e32 v96, 46, v72
	v_lshlrev_b32_e32 v6, 7, v95
	v_lshlrev_b32_e32 v5, 2, v5
	v_add3_u32 v127, s1, v6, v5
	v_bitop3_b32 v5, v96, 31, v1 bitop3:0x48
	v_or_b32_e32 v97, 48, v72
	v_lshlrev_b32_e32 v6, 7, v96
	v_lshlrev_b32_e32 v5, 2, v5
	v_add3_u32 v128, s1, v6, v5
	v_bitop3_b32 v5, v97, 31, v1 bitop3:0x48
	v_or_b32_e32 v98, 50, v72
	v_lshlrev_b32_e32 v6, 7, v97
	v_lshlrev_b32_e32 v5, 2, v5
	v_add3_u32 v129, s1, v6, v5
	v_bitop3_b32 v5, v98, 31, v1 bitop3:0x48
	v_or_b32_e32 v99, 52, v72
	v_lshlrev_b32_e32 v6, 7, v98
	v_lshlrev_b32_e32 v5, 2, v5
	v_add3_u32 v130, s1, v6, v5
	v_bitop3_b32 v5, v99, 31, v1 bitop3:0x48
	v_or_b32_e32 v100, 54, v72
	v_lshlrev_b32_e32 v6, 7, v99
	v_lshlrev_b32_e32 v5, 2, v5
	v_add3_u32 v131, s1, v6, v5
	v_bitop3_b32 v5, v100, 31, v1 bitop3:0x48
	v_or_b32_e32 v101, 56, v72
	v_lshlrev_b32_e32 v6, 7, v100
	v_lshlrev_b32_e32 v5, 2, v5
	v_add3_u32 v132, s1, v6, v5
	v_bitop3_b32 v5, v101, 31, v1 bitop3:0x48
	v_or_b32_e32 v102, 58, v72
	v_lshlrev_b32_e32 v6, 7, v101
	v_lshlrev_b32_e32 v5, 2, v5
	v_add3_u32 v133, s1, v6, v5
	v_bitop3_b32 v5, v102, 31, v1 bitop3:0x48
	v_or_b32_e32 v103, 60, v72
	v_lshlrev_b32_e32 v6, 7, v102
	v_lshlrev_b32_e32 v5, 2, v5
	v_add3_u32 v134, s1, v6, v5
	v_bitop3_b32 v5, v103, 31, v1 bitop3:0x48
	v_or_b32_e32 v104, 62, v72
	v_lshlrev_b32_e32 v6, 7, v103
	v_lshlrev_b32_e32 v5, 2, v5
	v_lshlrev_b32_e32 v3, 3, v36
	v_add3_u32 v135, s1, v6, v5
	v_bitop3_b32 v5, v104, 31, v1 bitop3:0x48
	v_lshrrev_b32_e32 v73, 3, v36
	v_and_b32_e32 v4, 56, v3
	v_lshlrev_b32_e32 v6, 7, v104
	v_lshlrev_b32_e32 v5, 2, v5
	v_add3_u32 v136, s1, v6, v5
	v_and_or_b32 v5, v3, 24, v73
	v_lshl_add_u32 v6, v4, 7, s1
	v_lshl_add_u32 v137, v5, 2, v6
	v_or_b32_e32 v5, 1, v4
	v_bitop3_b32 v7, v5, v73, 25 bitop3:0x6c
	v_lshl_add_u32 v8, v5, 7, s1
	v_lshl_add_u32 v138, v7, 2, v8
	v_or_b32_e32 v7, 2, v4
	v_bitop3_b32 v9, v7, v73, 26 bitop3:0x6c
	v_lshl_add_u32 v10, v7, 7, s1
	v_lshl_add_u32 v139, v9, 2, v10
	v_or_b32_e32 v9, 3, v4
	v_bitop3_b32 v11, v9, v73, 27 bitop3:0x6c
	v_lshl_add_u32 v12, v9, 7, s1
	v_lshl_add_u32 v140, v11, 2, v12
	v_or_b32_e32 v11, 4, v4
	v_bitop3_b32 v13, v11, v73, 28 bitop3:0x6c
	v_lshl_add_u32 v14, v11, 7, s1
	v_or_b32_e32 v142, 8, v73
	v_lshl_add_u32 v141, v13, 2, v14
	v_bitop3_b32 v13, v3, v142, 24 bitop3:0x6c
	v_lshl_add_u32 v143, v13, 2, v6
	v_bitop3_b32 v13, v5, v142, 25 bitop3:0x6c
	v_lshl_add_u32 v144, v13, 2, v8
	v_bitop3_b32 v13, v7, v142, 26 bitop3:0x6c
	v_lshl_add_u32 v145, v13, 2, v10
	v_bitop3_b32 v13, v9, v142, 27 bitop3:0x6c
	v_lshl_add_u32 v146, v13, 2, v12
	v_bitop3_b32 v13, v11, v142, 28 bitop3:0x6c
	v_or_b32_e32 v148, 16, v73
	v_lshl_add_u32 v147, v13, 2, v14
	v_bitop3_b32 v13, v3, v148, 24 bitop3:0x6c
	v_bitop3_b32 v3, v3, v73, 24 bitop3:0x4e
	v_or_b32_e32 v152, 24, v73
	v_lshl_add_u32 v151, v3, 2, v6
	v_bitop3_b32 v3, v5, v152, 25 bitop3:0x6c
	v_lshl_add_u32 v153, v3, 2, v8
	v_bitop3_b32 v3, v7, v148, 26 bitop3:0x6c
	v_lshl_add_u32 v154, v3, 2, v10
	v_bitop3_b32 v3, v7, v152, 26 bitop3:0x6c
	v_lshl_add_u32 v155, v3, 2, v10
	v_bitop3_b32 v3, v9, v148, 27 bitop3:0x6c
	v_lshl_add_u32 v156, v3, 2, v12
	v_bitop3_b32 v3, v9, v152, 27 bitop3:0x6c
	v_lshl_add_u32 v157, v3, 2, v12
	v_bitop3_b32 v3, v11, v148, 28 bitop3:0x6c
	v_lshl_add_u32 v158, v3, 2, v14
	v_bitop3_b32 v3, v11, v152, 28 bitop3:0x6c
	v_lshl_add_u32 v159, v3, 2, v14
	v_or_b32_e32 v3, 5, v4
	v_lshl_add_u32 v149, v13, 2, v6
	v_bitop3_b32 v13, v5, v148, 25 bitop3:0x6c
	v_bitop3_b32 v5, v3, v73, 29 bitop3:0x6c
	v_lshl_add_u32 v6, v3, 7, s1
	v_lshl_add_u32 v160, v5, 2, v6
	v_bitop3_b32 v5, v3, v142, 29 bitop3:0x6c
	v_lshl_add_u32 v161, v5, 2, v6
	v_bitop3_b32 v5, v3, v148, 29 bitop3:0x6c
	v_bitop3_b32 v3, v3, v152, 29 bitop3:0x6c
	v_lshl_add_u32 v163, v3, 2, v6
	v_or_b32_e32 v3, 6, v4
	v_lshl_add_u32 v162, v5, 2, v6
	v_bitop3_b32 v5, v3, v73, 30 bitop3:0x6c
	v_lshl_add_u32 v6, v3, 7, s1
	v_lshl_add_u32 v164, v5, 2, v6
	v_bitop3_b32 v5, v3, v142, 30 bitop3:0x6c
	v_lshl_add_u32 v165, v5, 2, v6
	v_bitop3_b32 v5, v3, v148, 30 bitop3:0x6c
	v_bitop3_b32 v3, v3, v152, 30 bitop3:0x6c
	v_lshl_add_u32 v167, v3, 2, v6
	v_or_b32_e32 v3, 7, v4
	v_lshl_add_u32 v166, v5, 2, v6
	v_lshl_add_u32 v6, v3, 7, s1
	s_lshl_b32 s1, s2, 3
	v_bitop3_b32 v5, v3, v73, 31 bitop3:0x6c
	s_add_i32 s23, s0, s1
	s_lshl_b32 s26, s94, 3
	v_lshl_add_u32 v168, v5, 2, v6
	v_bitop3_b32 v5, v3, v142, 31 bitop3:0x6c
	s_cmpk_lt_i32 s23, 0x2000
	v_lshl_add_u32 v169, v5, 2, v6
	v_bitop3_b32 v5, v3, v148, 31 bitop3:0x6c
	v_bitop3_b32 v3, v3, v152, 31 bitop3:0x6c
	s_cselect_b64 s[0:1], -1, 0
	s_lshl_b32 s27, s94, 4
	v_lshl_add_u32 v150, v13, 2, v8
	v_lshl_add_u32 v170, v5, 2, v6
	v_lshl_add_u32 v171, v3, 2, v6
	s_cmpk_gt_i32 s23, 0x1fff
	v_lshlrev_b32_e32 v2, 2, v2
	v_mov_b32_e32 v3, 0
	v_lshlrev_b32_e32 v4, 1, v4
	s_cbranch_scc1 .LBB0_45
	v_mov_b32_e32 v5, v3
	v_lshl_add_u64 v[8:9], s[16:17], 0, v[4:5]
	s_mov_b64 s[4:5], 0x6140000
	v_lshl_add_u64 v[6:7], s[12:13], 0, v[2:3]
	v_lshl_add_u64 v[8:9], v[8:9], 0, s[4:5]
	s_lshl_b32 s28, s23, 5
	s_lshl_b32 s29, s27, 5
	s_mov_b32 s30, s23
	s_branch .LBB0_43

.LBB0_180:
	s_andn2_b64 vcc, exec, s[0:1]
	v_readlane_b32 s0, v255, 36
	v_readlane_b32 s1, v255, 37
	s_xor_b64 s[0:1], s[0:1], -1
	v_writelane_b32 v255, s0, 51
	s_nop 1
	v_writelane_b32 v255, s1, 52
	s_cbranch_vccnz .LBB0_330
	v_mov_b32_e32 v10, v195
	v_readlane_b32 s20, v255, 51
	v_readfirstlane_b32 s0, v10
	v_and_b32_e32 v37, 63, v10
	s_ashr_i32 s0, s0, 6
	v_readlane_b32 s1, v255, 25
	v_readlane_b32 s21, v255, 52
	s_add_i32 s38, s0, s1
	s_andn2_b64 vcc, exec, s[20:21]
	v_lshlrev_b32_e32 v36, 3, v37
	s_cbranch_vccnz .LBB0_243
	s_mov_b32 s100, s0

.Lstg1_done:
	v_lshrrev_b32_e32 v11, 5, v37
	s_lshl_b32 s0, s0, 14
	v_bitop3_b32 v2, v11, v10, 31 bitop3:0x78
	s_add_i32 s20, s0, 0
	v_and_b32_e32 v0, 31, v10
	v_lshlrev_b32_e32 v3, 7, v11
	v_lshlrev_b32_e32 v2, 2, v2
	v_or_b32_e32 v13, 2, v11
	v_add3_u32 v46, s20, v3, v2
	v_bitop3_b32 v3, v11, v0, 2 bitop3:0x36
	v_lshlrev_b32_e32 v4, 7, v13
	v_lshlrev_b32_e32 v3, 2, v3
	v_or_b32_e32 v14, 4, v11
	v_add3_u32 v47, s20, v4, v3
	v_bitop3_b32 v3, v11, v0, 4 bitop3:0x36
	v_lshlrev_b32_e32 v4, 7, v14
	v_lshlrev_b32_e32 v3, 2, v3
	v_or_b32_e32 v15, 6, v11
	v_add3_u32 v48, s20, v4, v3
	v_bitop3_b32 v3, v11, v0, 6 bitop3:0x36
	v_lshlrev_b32_e32 v4, 7, v15
	v_lshlrev_b32_e32 v3, 2, v3
	v_or_b32_e32 v16, 8, v11
	v_add3_u32 v49, s20, v4, v3
	v_bitop3_b32 v3, v11, v0, 8 bitop3:0x36
	v_lshlrev_b32_e32 v4, 7, v16
	v_lshlrev_b32_e32 v3, 2, v3
	v_or_b32_e32 v17, 10, v11
	v_add3_u32 v50, s20, v4, v3
	v_bitop3_b32 v3, v11, v0, 10 bitop3:0x36
	v_lshlrev_b32_e32 v4, 7, v17
	v_lshlrev_b32_e32 v3, 2, v3
	v_or_b32_e32 v18, 12, v11
	v_add3_u32 v51, s20, v4, v3
	v_bitop3_b32 v3, v11, v0, 12 bitop3:0x36
	v_lshlrev_b32_e32 v4, 7, v18
	v_lshlrev_b32_e32 v3, 2, v3
	v_or_b32_e32 v19, 14, v11
	v_add3_u32 v52, s20, v4, v3
	v_bitop3_b32 v3, v11, v0, 14 bitop3:0x36
	v_lshlrev_b32_e32 v4, 7, v19
	v_lshlrev_b32_e32 v3, 2, v3
	v_or_b32_e32 v20, 16, v11
	v_add3_u32 v53, s20, v4, v3
	v_bitop3_b32 v3, v11, v0, 16 bitop3:0x36
	v_lshlrev_b32_e32 v4, 7, v20
	v_lshlrev_b32_e32 v3, 2, v3
	v_or_b32_e32 v21, 18, v11
	v_add3_u32 v54, s20, v4, v3
	v_bitop3_b32 v3, v11, v0, 18 bitop3:0x36
	v_lshlrev_b32_e32 v4, 7, v21
	v_lshlrev_b32_e32 v3, 2, v3
	v_or_b32_e32 v22, 20, v11
	v_add3_u32 v55, s20, v4, v3
	v_bitop3_b32 v3, v11, v0, 20 bitop3:0x36
	v_lshlrev_b32_e32 v4, 7, v22
	v_lshlrev_b32_e32 v3, 2, v3
	v_or_b32_e32 v23, 22, v11
	v_add3_u32 v56, s20, v4, v3
	v_bitop3_b32 v3, v11, v0, 22 bitop3:0x36
	v_lshlrev_b32_e32 v4, 7, v23
	v_lshlrev_b32_e32 v3, 2, v3
	v_or_b32_e32 v24, 24, v11
	v_add3_u32 v57, s20, v4, v3
	v_bitop3_b32 v3, v11, v0, 24 bitop3:0x36
	v_lshlrev_b32_e32 v4, 7, v24
	v_lshlrev_b32_e32 v3, 2, v3
	v_or_b32_e32 v25, 26, v11
	v_add3_u32 v58, s20, v4, v3
	v_bitop3_b32 v3, v11, v0, 26 bitop3:0x36
	v_lshlrev_b32_e32 v4, 7, v25
	v_lshlrev_b32_e32 v3, 2, v3
	v_or_b32_e32 v26, 28, v11
	v_add3_u32 v59, s20, v4, v3
	v_bitop3_b32 v3, v11, v0, 28 bitop3:0x36
	v_lshlrev_b32_e32 v4, 7, v26
	v_lshlrev_b32_e32 v3, 2, v3
	v_or_b32_e32 v27, 30, v11
	v_add3_u32 v60, s20, v4, v3
	v_bitop3_b32 v3, v11, v0, 30 bitop3:0x36
	v_or_b32_e32 v28, 32, v11
	v_lshlrev_b32_e32 v4, 7, v27
	v_lshlrev_b32_e32 v3, 2, v3
	v_or_b32_e32 v29, 34, v11
	v_add3_u32 v61, s20, v4, v3
	v_lshlrev_b32_e32 v3, 7, v28
	v_add3_u32 v62, s20, v3, v2
	v_bitop3_b32 v2, v29, 31, v10 bitop3:0x48
	v_or_b32_e32 v30, 36, v11
	v_lshlrev_b32_e32 v3, 7, v29
	v_lshlrev_b32_e32 v2, 2, v2
	v_add3_u32 v63, s20, v3, v2
	v_bitop3_b32 v2, v30, 31, v10 bitop3:0x48
	v_or_b32_e32 v31, 38, v11
	v_lshlrev_b32_e32 v3, 7, v30
	v_lshlrev_b32_e32 v2, 2, v2
	v_add3_u32 v64, s20, v3, v2
	v_bitop3_b32 v2, v31, 31, v10 bitop3:0x48
	v_or_b32_e32 v32, 40, v11
	v_lshlrev_b32_e32 v3, 7, v31
	v_lshlrev_b32_e32 v2, 2, v2
	v_add3_u32 v65, s20, v3, v2
	v_bitop3_b32 v2, v32, 31, v10 bitop3:0x48
	v_or_b32_e32 v33, 42, v11
	v_lshlrev_b32_e32 v3, 7, v32
	v_lshlrev_b32_e32 v2, 2, v2
	v_add3_u32 v66, s20, v3, v2
	v_bitop3_b32 v2, v33, 31, v10 bitop3:0x48
	v_or_b32_e32 v34, 44, v11
	v_lshlrev_b32_e32 v3, 7, v33
	v_lshlrev_b32_e32 v2, 2, v2
	v_add3_u32 v67, s20, v3, v2
	v_bitop3_b32 v2, v34, 31, v10 bitop3:0x48
	v_or_b32_e32 v35, 46, v11
	v_lshlrev_b32_e32 v3, 7, v34
	v_lshlrev_b32_e32 v2, 2, v2
	v_add3_u32 v68, s20, v3, v2
	v_bitop3_b32 v2, v35, 31, v10 bitop3:0x48
	v_or_b32_e32 v38, 48, v11
	v_lshlrev_b32_e32 v3, 7, v35
	v_lshlrev_b32_e32 v2, 2, v2
	v_add3_u32 v69, s20, v3, v2
	v_bitop3_b32 v2, v38, 31, v10 bitop3:0x48
	v_or_b32_e32 v39, 50, v11
	v_lshlrev_b32_e32 v3, 7, v38
	v_lshlrev_b32_e32 v2, 2, v2
	v_add3_u32 v70, s20, v3, v2
	v_bitop3_b32 v2, v39, 31, v10 bitop3:0x48
	v_or_b32_e32 v40, 52, v11
	v_lshlrev_b32_e32 v3, 7, v39
	v_lshlrev_b32_e32 v2, 2, v2
	v_add3_u32 v71, s20, v3, v2
	v_bitop3_b32 v2, v40, 31, v10 bitop3:0x48
	v_or_b32_e32 v41, 54, v11
	v_lshlrev_b32_e32 v3, 7, v40
	v_lshlrev_b32_e32 v2, 2, v2
	v_add3_u32 v72, s20, v3, v2
	v_bitop3_b32 v2, v41, 31, v10 bitop3:0x48
	v_or_b32_e32 v42, 56, v11
	v_lshlrev_b32_e32 v3, 7, v41
	v_lshlrev_b32_e32 v2, 2, v2
	v_add3_u32 v73, s20, v3, v2
	v_bitop3_b32 v2, v42, 31, v10 bitop3:0x48
	v_or_b32_e32 v43, 58, v11
	v_lshlrev_b32_e32 v3, 7, v42
	v_lshlrev_b32_e32 v2, 2, v2
	v_add3_u32 v74, s20, v3, v2
	v_bitop3_b32 v2, v43, 31, v10 bitop3:0x48
	v_or_b32_e32 v44, 60, v11
	v_lshlrev_b32_e32 v3, 7, v43
	v_lshlrev_b32_e32 v2, 2, v2
	v_add3_u32 v75, s20, v3, v2
	v_bitop3_b32 v2, v44, 31, v10 bitop3:0x48
	v_or_b32_e32 v45, 62, v11
	v_lshlrev_b32_e32 v3, 7, v44
	v_lshlrev_b32_e32 v2, 2, v2
	v_add3_u32 v76, s20, v3, v2
	v_bitop3_b32 v2, v45, 31, v10 bitop3:0x48
	v_lshrrev_b32_e32 v12, 3, v37
	v_and_b32_e32 v1, 56, v36
	v_lshlrev_b32_e32 v3, 7, v45
	v_lshlrev_b32_e32 v2, 2, v2
	v_add3_u32 v77, s20, v3, v2
	v_and_or_b32 v2, v36, 24, v12
	v_lshl_add_u32 v3, v1, 7, s20
	v_lshl_add_u32 v78, v2, 2, v3
	v_or_b32_e32 v2, 1, v1
	v_bitop3_b32 v4, v2, v12, 25 bitop3:0x6c
	v_lshl_add_u32 v5, v2, 7, s20
	v_lshl_add_u32 v79, v4, 2, v5
	v_or_b32_e32 v4, 2, v1
	v_bitop3_b32 v6, v4, v12, 26 bitop3:0x6c
	v_lshl_add_u32 v7, v4, 7, s20
	v_or_b32_e32 v86, 8, v12
	v_or_b32_e32 v95, 16, v12
	v_or_b32_e32 v104, 24, v12
	v_lshl_add_u32 v80, v6, 2, v7
	v_or_b32_e32 v6, 3, v1
	v_bitop3_b32 v88, v2, v86, 25 bitop3:0x6c
	v_bitop3_b32 v97, v2, v95, 25 bitop3:0x6c
	v_bitop3_b32 v2, v2, v104, 25 bitop3:0x6c
	v_bitop3_b32 v8, v6, v12, 27 bitop3:0x6c
	v_lshl_add_u32 v9, v6, 7, s20
	v_lshl_add_u32 v106, v2, 2, v5
	v_bitop3_b32 v2, v4, v104, 26 bitop3:0x6c
	v_lshl_add_u32 v81, v8, 2, v9
	v_or_b32_e32 v8, 4, v1
	v_lshl_add_u32 v107, v2, 2, v7
	v_bitop3_b32 v2, v6, v104, 27 bitop3:0x6c
	v_bitop3_b32 v82, v8, v12, 28 bitop3:0x6c
	v_lshl_add_u32 v109, v8, 7, s20
	v_or_b32_e32 v110, 5, v1
	v_bitop3_b32 v91, v8, v86, 28 bitop3:0x6c
	v_bitop3_b32 v100, v8, v95, 28 bitop3:0x6c
	v_lshl_add_u32 v108, v2, 2, v9
	v_bitop3_b32 v2, v8, v104, 28 bitop3:0x6c
	v_lshl_add_u32 v82, v82, 2, v109
	v_lshl_add_u32 v111, v110, 7, s20
	v_or_b32_e32 v112, 6, v1
	v_lshl_add_u32 v91, v91, 2, v109
	v_lshl_add_u32 v100, v100, 2, v109
	v_lshl_add_u32 v109, v2, 2, v109
	v_bitop3_b32 v2, v110, v104, 29 bitop3:0x6c
	v_bitop3_b32 v83, v110, v12, 29 bitop3:0x6c
	v_lshl_add_u32 v113, v112, 7, s20
	v_or_b32_e32 v114, 7, v1
	v_bitop3_b32 v92, v110, v86, 29 bitop3:0x6c
	v_bitop3_b32 v101, v110, v95, 29 bitop3:0x6c
	v_lshl_add_u32 v110, v2, 2, v111
	v_bitop3_b32 v2, v112, v104, 30 bitop3:0x6c
	s_cmpk_lt_i32 s38, 0x2000
	v_lshl_add_u32 v83, v83, 2, v111
	v_bitop3_b32 v84, v112, v12, 30 bitop3:0x6c
	v_bitop3_b32 v85, v114, v12, 31 bitop3:0x6c
	v_lshl_add_u32 v115, v114, 7, s20
	v_bitop3_b32 v87, v36, v86, 24 bitop3:0x6c
	v_bitop3_b32 v89, v4, v86, 26 bitop3:0x6c
	v_bitop3_b32 v90, v6, v86, 27 bitop3:0x6c
	v_lshl_add_u32 v92, v92, 2, v111
	v_bitop3_b32 v93, v112, v86, 30 bitop3:0x6c
	v_bitop3_b32 v94, v114, v86, 31 bitop3:0x6c
	v_bitop3_b32 v96, v36, v95, 24 bitop3:0x6c
	v_bitop3_b32 v98, v4, v95, 26 bitop3:0x6c
	v_bitop3_b32 v99, v6, v95, 27 bitop3:0x6c
	v_lshl_add_u32 v101, v101, 2, v111
	v_bitop3_b32 v102, v112, v95, 30 bitop3:0x6c
	v_bitop3_b32 v103, v114, v95, 31 bitop3:0x6c
	v_bitop3_b32 v105, v36, v12, 24 bitop3:0x4e
	v_lshl_add_u32 v111, v2, 2, v113
	v_bitop3_b32 v2, v114, v104, 31 bitop3:0x6c
	s_cselect_b64 s[0:1], -1, 0
	s_cmpk_gt_i32 s38, 0x1fff
	v_lshl_add_u32 v84, v84, 2, v113
	v_lshl_add_u32 v85, v85, 2, v115
	v_lshl_add_u32 v87, v87, 2, v3
	v_lshl_add_u32 v88, v88, 2, v5
	v_lshl_add_u32 v89, v89, 2, v7
	v_lshl_add_u32 v90, v90, 2, v9
	v_lshl_add_u32 v93, v93, 2, v113
	v_lshl_add_u32 v94, v94, 2, v115
	v_lshl_add_u32 v96, v96, 2, v3
	v_lshl_add_u32 v97, v97, 2, v5
	v_lshl_add_u32 v98, v98, 2, v7
	v_lshl_add_u32 v99, v99, 2, v9
	v_lshl_add_u32 v102, v102, 2, v113
	v_lshl_add_u32 v103, v103, 2, v115
	v_lshl_add_u32 v105, v105, 2, v3
	v_lshl_add_u32 v112, v2, 2, v115
	v_lshlrev_b32_e32 v192, 2, v0
	v_lshlrev_b32_e32 v0, 1, v1
	s_cbranch_scc1 .LBB0_187
	v_readlane_b32 s20, v251, 1
	v_readlane_b32 s21, v251, 2
	v_mov_b32_e32 v1, v193
	s_lshl_b32 s28, s38, 5
	v_lshl_add_u64 v[2:3], s[20:21], 0, v[192:193]
	v_readlane_b32 s20, v250, 63
	v_readlane_b32 s21, v251, 0
	s_lshl_b32 s34, s12, 5
	s_mov_b32 s35, s38
	v_lshl_add_u64 v[4:5], s[20:21], 0, v[0:1]
	s_branch .LBB0_185

	.amdhsa_kernel _Z4mega6Params
		.amdhsa_group_segment_fixed_size 0
		.amdhsa_private_segment_fixed_size 0
		.amdhsa_kernarg_size 576
		.amdhsa_user_sgpr_count 2
		.amdhsa_user_sgpr_dispatch_ptr 0
		.amdhsa_user_sgpr_queue_ptr 0
		.amdhsa_user_sgpr_kernarg_segment_ptr 1
		.amdhsa_user_sgpr_dispatch_id 0
		.amdhsa_user_sgpr_kernarg_preload_length 0
		.amdhsa_user_sgpr_kernarg_preload_offset 0
		.amdhsa_user_sgpr_private_segment_size 0
		.amdhsa_uses_dynamic_stack 0
		.amdhsa_enable_private_segment 0
		.amdhsa_system_sgpr_workgroup_id_x 1
		.amdhsa_system_sgpr_workgroup_id_y 0
		.amdhsa_system_sgpr_workgroup_id_z 0
		.amdhsa_system_sgpr_workgroup_info 0
		.amdhsa_system_vgpr_workitem_id 2
		.amdhsa_next_free_vgpr 256
		.amdhsa_next_free_sgpr 102
		.amdhsa_accum_offset 256
		.amdhsa_reserve_vcc 1
		.amdhsa_float_round_mode_32 0
		.amdhsa_float_round_mode_16_64 0
		.amdhsa_float_denorm_mode_32 3
		.amdhsa_float_denorm_mode_16_64 3
		.amdhsa_dx10_clamp 1
		.amdhsa_ieee_mode 1
		.amdhsa_fp16_overflow 0
		.amdhsa_tg_split 0
		.amdhsa_exception_fp_ieee_invalid_op 0
		.amdhsa_exception_fp_denorm_src 0
		.amdhsa_exception_fp_ieee_div_zero 0
		.amdhsa_exception_fp_ieee_overflow 0
		.amdhsa_exception_fp_ieee_underflow 0
		.amdhsa_exception_fp_ieee_inexact 0
		.amdhsa_exception_int_div_zero 0
	.end_amdhsa_kernel

amdhsa.kernels:
  - .agpr_count:     0
    .args:
      - .offset:         0
        .size:           320
        .value_kind:     by_value
      - .offset:         320
        .size:           4
        .value_kind:     hidden_block_count_x
      - .offset:         324
        .size:           4
        .value_kind:     hidden_block_count_y
      - .offset:         328
        .size:           4
        .value_kind:     hidden_block_count_z
      - .offset:         332
        .size:           2
        .value_kind:     hidden_group_size_x
      - .offset:         334
        .size:           2
        .value_kind:     hidden_group_size_y
      - .offset:         336
        .size:           2
        .value_kind:     hidden_group_size_z
      - .offset:         338
        .size:           2
        .value_kind:     hidden_remainder_x
      - .offset:         340
        .size:           2
        .value_kind:     hidden_remainder_y
      - .offset:         342
        .size:           2
        .value_kind:     hidden_remainder_z
      - .offset:         360
        .size:           8
        .value_kind:     hidden_global_offset_x
      - .offset:         368
        .size:           8
        .value_kind:     hidden_global_offset_y
      - .offset:         376
        .size:           8
        .value_kind:     hidden_global_offset_z
      - .offset:         384
        .size:           2
        .value_kind:     hidden_grid_dims
      - .offset:         408
        .size:           8
        .value_kind:     hidden_multigrid_sync_arg
      - .offset:         440
        .size:           4
        .value_kind:     hidden_dynamic_lds_size
    .group_segment_fixed_size: 0
    .kernarg_segment_align: 8
    .kernarg_segment_size: 576
    .language:       OpenCL C
    .language_version:
      - 2
      - 0
    .max_flat_workgroup_size: 512
    .name:           _Z4mega6Params
    .private_segment_fixed_size: 0
    .sgpr_count:     108
    .sgpr_spill_count: 379
    .symbol:         _Z4mega6Params.kd
    .uniform_work_group_size: 1
    .uses_dynamic_stack: false
    .vgpr_count:     256
    .vgpr_spill_count: 0
    .wavefront_size: 64
